# FFN gate/up epilogue float math rewritten by hand: out = (a*g)*r^2 * rcp(1+exp2(a*(-log2e*r))), 7 VALU per element instead of ~9.5 (no register-pairing movs / packed fma)
# speedup vs baseline: 1.0051x; 1.0049x over previous
; __host__ __device__ __forceinline__ size_t tiled_off(int row, int col, int K) { return ((size_t)(row >> 7) * (K >> 6) + (col >> 6)) * 8192 + (lds_byte(row & 127, col & 63) >> 1); }
; __device__ __forceinline__ unsigned cvt_pk_bf16(float lo, float hi) { unsigned r; asm volatile("v_cvt_pk_bf16_f32 %0, %1, %2" : "=v"(r) : "v"(lo), "v"(hi)); return r; }
; __device__ __forceinline__ float fast_sigmoid(float x) { return __builtin_amdgcn_rcpf(1.0f + __builtin_amdgcn_exp2f(x * -1.4426950408889634f)); }
;     __device__ __forceinline__ void operator()(const f32x4 (&acc)[2][2][4][2], const Unit& u, int wr, int wc, int fr, int fq, const PG8_LAS float* rtab) const {
;         const int row0 = u.pm * BM + wr * 64 + fr, lcol = u.pn * HALF + wc * 32 + 8 * fq;
;         float rs[2][4]; load_rstd(rtab, wr, fr, rs);
;         f32x4 bv[2], bg[2];
; #pragma unroll
;         for (int n = 0; n < 2; ++n) { bv[n] = (MODE == 0) ? *(const f32x4*)(b0 + lcol + 4 * n) : (f32x4){0.f, 0.f, 0.f, 0.f}; bg[n] = (MODE == 0) ? *(const f32x4*)(b1 + lcol + 4 * n) : (f32x4){0.f, 0.f, 0.f, 0.f}; }
; #pragma unroll
;         for (int ai = 0; ai < 2; ++ai)
; #pragma unroll
;             for (int m = 0; m < 4; ++m) { const float r = rs[ai][m]; float o[8];
; #pragma unroll
;                 for (int n = 0; n < 2; ++n) { const f32x4 a = acc[ai][0][m][n] * r + bv[n], g = acc[ai][1][m][n] * r + bg[n];
; #pragma unroll
;                     for (int e = 0; e < 4; ++e) o[4 * n + e] = (MODE == 0) ? a[e] * fast_sigmoid(g[e]) : a[e] * fast_sigmoid(a[e]) * g[e]; }
;                 u32x4 w; w.x = cvt_pk_bf16(o[0], o[1]); w.y = cvt_pk_bf16(o[2], o[3]); w.z = cvt_pk_bf16(o[4], o[5]); w.w = cvt_pk_bf16(o[6], o[7]);
;                 if (MODE == 1) *(u32x4*)(O + tiled_off(row0 + ai * HALF + m * 16, lcol, ldc)) = w;
.LBB0_793:
	s_lshl_b32 s53, s61, 10
	s_and_b32 s55, s53, 0x400
	v_add_u32_e32 v130, s55, v146
	ds_read2_b32 v[152:153], v130 offset1:16
	ds_read2_b32 v[140:141], v130 offset0:32 offset1:48
	ds_read2_b32 v[138:139], v130 offset0:128 offset1:144
	ds_read2_b32 v[136:137], v130 offset0:160 offset1:176
	s_waitcnt lgkmcnt(0)
	s_lshl_b32 s53, s60, 8
	s_add_i32 s53, s53, s38
	v_or_b32_e32 v151, s53, v142
	v_mul_f32_e32 v224, 0xbfb8aa3b, v152
	v_mul_f32_e32 v225, v152, v152
	v_mul_f32_e32 v234, v124, v224
	v_mul_f32_e32 v235, v125, v224
	v_mul_f32_e32 v236, v126, v224
	v_mul_f32_e32 v237, v127, v224
	v_mul_f32_e32 v238, v116, v224
	v_mul_f32_e32 v239, v117, v224
	v_mul_f32_e32 v240, v118, v224
	v_mul_f32_e32 v241, v119, v224
	v_mul_f32_e32 v226, v124, v120
	v_mul_f32_e32 v227, v125, v121
	v_mul_f32_e32 v228, v126, v122
	v_mul_f32_e32 v229, v127, v123
	v_mul_f32_e32 v230, v116, v112
	v_mul_f32_e32 v231, v117, v113
	v_mul_f32_e32 v232, v118, v114
	v_mul_f32_e32 v233, v119, v115
	v_exp_f32_e32 v234, v234
	v_exp_f32_e32 v235, v235
	v_exp_f32_e32 v236, v236
	v_exp_f32_e32 v237, v237
	v_exp_f32_e32 v238, v238
	v_exp_f32_e32 v239, v239
	v_exp_f32_e32 v240, v240
	v_exp_f32_e32 v241, v241
	v_mul_f32_e32 v226, v226, v225
	v_mul_f32_e32 v227, v227, v225
	v_mul_f32_e32 v228, v228, v225
	v_mul_f32_e32 v229, v229, v225
	v_mul_f32_e32 v230, v230, v225
	v_mul_f32_e32 v231, v231, v225
	v_mul_f32_e32 v232, v232, v225
	v_mul_f32_e32 v233, v233, v225
	v_add_f32_e32 v234, 1.0, v234
	v_add_f32_e32 v235, 1.0, v235
	v_add_f32_e32 v236, 1.0, v236
	v_add_f32_e32 v237, 1.0, v237
	v_add_f32_e32 v238, 1.0, v238
	v_add_f32_e32 v239, 1.0, v239
	v_add_f32_e32 v240, 1.0, v240
	v_add_f32_e32 v241, 1.0, v241
	v_rcp_f32_e32 v234, v234
	v_rcp_f32_e32 v235, v235
	v_rcp_f32_e32 v236, v236
	v_rcp_f32_e32 v237, v237
	v_rcp_f32_e32 v238, v238
	v_rcp_f32_e32 v239, v239
	v_rcp_f32_e32 v240, v240
	v_rcp_f32_e32 v241, v241
	v_mul_f32_e32 v226, v226, v234
	v_mul_f32_e32 v227, v227, v235
	v_mul_f32_e32 v228, v228, v236
	v_mul_f32_e32 v229, v229, v237
	v_mul_f32_e32 v230, v230, v238
	v_mul_f32_e32 v231, v231, v239
	v_mul_f32_e32 v232, v232, v240
	v_mul_f32_e32 v233, v233, v241
	v_cvt_pk_bf16_f32 v242, v226, v227
	v_cvt_pk_bf16_f32 v243, v228, v229
	v_cvt_pk_bf16_f32 v244, v230, v231
	v_cvt_pk_bf16_f32 v245, v232, v233
	v_lshlrev_b32_e32 v116, 6, v151
	v_and_or_b32 v118, v116, s40, v143
	v_lshlrev_b32_e32 v116, 2, v151
	v_and_b32_e32 v119, 32, v116
	s_lshl_b32 s55, s68, 7
	s_or_b32 s55, s55, s39
	s_ashr_i32 s60, s55, 6
	s_ashr_i32 s55, s53, 7
	s_mul_i32 s55, s55, 44
	s_ashr_i32 s61, s60, 31
	s_ashr_i32 s69, s55, 31
	s_add_u32 s68, s55, s60
	s_addc_u32 s69, s69, s61
	s_lshl_b64 s[68:69], s[68:69], 14
	s_add_u32 s68, s14, s68
	v_bitop3_b32 v120, v118, s42, v119 bitop3:0xde
	s_addc_u32 s69, s15, s69
	global_store_dwordx4 v120, v[242:245], s[68:69]
	s_or_b32 s55, s53, 16
	s_lshr_b32 s55, s55, 3
	s_and_b32 s55, s55, 10
	s_or_b32 s55, s55, s41
	s_lshl_b32 s55, s55, 10
	v_mul_f32_e32 v224, 0xbfb8aa3b, v140
	v_mul_f32_e32 v225, v140, v140
	v_mul_f32_e32 v234, v92, v224
	v_mul_f32_e32 v235, v93, v224
	v_mul_f32_e32 v236, v94, v224
	v_mul_f32_e32 v237, v95, v224
	v_mul_f32_e32 v238, v84, v224
	v_mul_f32_e32 v239, v85, v224
	v_mul_f32_e32 v240, v86, v224
	v_mul_f32_e32 v241, v87, v224
	v_mul_f32_e32 v226, v92, v88
	v_mul_f32_e32 v227, v93, v89
	v_mul_f32_e32 v228, v94, v90
	v_mul_f32_e32 v229, v95, v91
	v_mul_f32_e32 v230, v84, v80
	v_mul_f32_e32 v231, v85, v81
	v_mul_f32_e32 v232, v86, v82
	v_mul_f32_e32 v233, v87, v83
	v_exp_f32_e32 v234, v234
	v_exp_f32_e32 v235, v235
	v_exp_f32_e32 v236, v236
	v_exp_f32_e32 v237, v237
	v_exp_f32_e32 v238, v238
	v_exp_f32_e32 v239, v239
	v_exp_f32_e32 v240, v240
	v_exp_f32_e32 v241, v241
	v_mul_f32_e32 v226, v226, v225
	v_mul_f32_e32 v227, v227, v225
	v_mul_f32_e32 v228, v228, v225
	v_mul_f32_e32 v229, v229, v225
	v_mul_f32_e32 v230, v230, v225
	v_mul_f32_e32 v231, v231, v225
	v_mul_f32_e32 v232, v232, v225
	v_mul_f32_e32 v233, v233, v225
	v_add_f32_e32 v234, 1.0, v234
	v_add_f32_e32 v235, 1.0, v235
	v_add_f32_e32 v236, 1.0, v236
	v_add_f32_e32 v237, 1.0, v237
	v_add_f32_e32 v238, 1.0, v238
	v_add_f32_e32 v239, 1.0, v239
	v_add_f32_e32 v240, 1.0, v240
	v_add_f32_e32 v241, 1.0, v241
	v_rcp_f32_e32 v234, v234
	v_rcp_f32_e32 v235, v235
	v_rcp_f32_e32 v236, v236
	v_rcp_f32_e32 v237, v237
	v_rcp_f32_e32 v238, v238
	v_rcp_f32_e32 v239, v239
	v_rcp_f32_e32 v240, v240
	v_rcp_f32_e32 v241, v241
	v_mul_f32_e32 v226, v226, v234
	v_mul_f32_e32 v227, v227, v235
	v_mul_f32_e32 v228, v228, v236
	v_mul_f32_e32 v229, v229, v237
	v_mul_f32_e32 v230, v230, v238
	v_mul_f32_e32 v231, v231, v239
	v_mul_f32_e32 v232, v232, v240
	v_mul_f32_e32 v233, v233, v241
	v_cvt_pk_bf16_f32 v250, v226, v227
	v_cvt_pk_bf16_f32 v251, v228, v229
	v_cvt_pk_bf16_f32 v252, v230, v231
	v_cvt_pk_bf16_f32 v253, v232, v233
	v_bitop3_b32 v93, v118, s55, v119 bitop3:0xde
	v_mul_f32_e32 v224, 0xbfb8aa3b, v153
	v_mul_f32_e32 v225, v153, v153
	v_mul_f32_e32 v234, v108, v224
	v_mul_f32_e32 v235, v109, v224
	v_mul_f32_e32 v236, v110, v224
	v_mul_f32_e32 v237, v111, v224
	v_mul_f32_e32 v238, v100, v224
	v_mul_f32_e32 v239, v101, v224
	v_mul_f32_e32 v240, v102, v224
	v_mul_f32_e32 v241, v103, v224
	v_mul_f32_e32 v226, v108, v104
	v_mul_f32_e32 v227, v109, v105
	v_mul_f32_e32 v228, v110, v106
	v_mul_f32_e32 v229, v111, v107
	v_mul_f32_e32 v230, v100, v96
	v_mul_f32_e32 v231, v101, v97
	v_mul_f32_e32 v232, v102, v98
	v_mul_f32_e32 v233, v103, v99
	v_exp_f32_e32 v234, v234
	v_exp_f32_e32 v235, v235
	v_exp_f32_e32 v236, v236
	v_exp_f32_e32 v237, v237
	v_exp_f32_e32 v238, v238
	v_exp_f32_e32 v239, v239
	v_exp_f32_e32 v240, v240
; __host__ __device__ __forceinline__ size_t tiled_off(int row, int col, int K) { return ((size_t)(row >> 7) * (K >> 6) + (col >> 6)) * 8192 + (lds_byte(row & 127, col & 63) >> 1); }
; __device__ __forceinline__ unsigned cvt_pk_bf16(float lo, float hi) { unsigned r; asm volatile("v_cvt_pk_bf16_f32 %0, %1, %2" : "=v"(r) : "v"(lo), "v"(hi)); return r; }
; __device__ __forceinline__ float fast_sigmoid(float x) { return __builtin_amdgcn_rcpf(1.0f + __builtin_amdgcn_exp2f(x * -1.4426950408889634f)); }
;     __device__ __forceinline__ void operator()(const f32x4 (&acc)[2][2][4][2], const Unit& u, int wr, int wc, int fr, int fq, const PG8_LAS float* rtab) const {
;         const int row0 = u.pm * BM + wr * 64 + fr, lcol = u.pn * HALF + wc * 32 + 8 * fq;
;         float rs[2][4]; load_rstd(rtab, wr, fr, rs);
;         f32x4 bv[2], bg[2];
; #pragma unroll
;         for (int n = 0; n < 2; ++n) { bv[n] = (MODE == 0) ? *(const f32x4*)(b0 + lcol + 4 * n) : (f32x4){0.f, 0.f, 0.f, 0.f}; bg[n] = (MODE == 0) ? *(const f32x4*)(b1 + lcol + 4 * n) : (f32x4){0.f, 0.f, 0.f, 0.f}; }
; #pragma unroll
;         for (int ai = 0; ai < 2; ++ai)
; #pragma unroll
;             for (int m = 0; m < 4; ++m) { const float r = rs[ai][m]; float o[8];
; #pragma unroll
;                 for (int n = 0; n < 2; ++n) { const f32x4 a = acc[ai][0][m][n] * r + bv[n], g = acc[ai][1][m][n] * r + bg[n];
; #pragma unroll
;                     for (int e = 0; e < 4; ++e) o[4 * n + e] = (MODE == 0) ? a[e] * fast_sigmoid(g[e]) : a[e] * fast_sigmoid(a[e]) * g[e]; }
;                 u32x4 w; w.x = cvt_pk_bf16(o[0], o[1]); w.y = cvt_pk_bf16(o[2], o[3]); w.z = cvt_pk_bf16(o[4], o[5]); w.w = cvt_pk_bf16(o[6], o[7]);
;                 if (MODE == 1) *(u32x4*)(O + tiled_off(row0 + ai * HALF + m * 16, lcol, ldc)) = w;
	v_exp_f32_e32 v241, v241
	v_mul_f32_e32 v226, v226, v225
	v_mul_f32_e32 v227, v227, v225
	v_mul_f32_e32 v228, v228, v225
	v_mul_f32_e32 v229, v229, v225
	v_mul_f32_e32 v230, v230, v225
	v_mul_f32_e32 v231, v231, v225
	v_mul_f32_e32 v232, v232, v225
	v_mul_f32_e32 v233, v233, v225
	v_add_f32_e32 v234, 1.0, v234
	v_add_f32_e32 v235, 1.0, v235
	v_add_f32_e32 v236, 1.0, v236
	v_add_f32_e32 v237, 1.0, v237
	v_add_f32_e32 v238, 1.0, v238
	v_add_f32_e32 v239, 1.0, v239
	v_add_f32_e32 v240, 1.0, v240
	v_add_f32_e32 v241, 1.0, v241
	v_rcp_f32_e32 v234, v234
	v_rcp_f32_e32 v235, v235
	v_rcp_f32_e32 v236, v236
	v_rcp_f32_e32 v237, v237
	v_rcp_f32_e32 v238, v238
	v_rcp_f32_e32 v239, v239
	v_rcp_f32_e32 v240, v240
	v_rcp_f32_e32 v241, v241
	v_mul_f32_e32 v226, v226, v234
	v_mul_f32_e32 v227, v227, v235
	v_mul_f32_e32 v228, v228, v236
	v_mul_f32_e32 v229, v229, v237
	v_mul_f32_e32 v230, v230, v238
	v_mul_f32_e32 v231, v231, v239
	v_mul_f32_e32 v232, v232, v240
	v_mul_f32_e32 v233, v233, v241
	v_cvt_pk_bf16_f32 v246, v226, v227
	v_cvt_pk_bf16_f32 v247, v228, v229
	v_cvt_pk_bf16_f32 v248, v230, v231
	v_cvt_pk_bf16_f32 v249, v232, v233
	global_store_dwordx4 v93, v[246:249], s[68:69]
	s_or_b32 s55, s53, 32
	s_lshr_b32 s55, s55, 3
	s_and_b32 s55, s55, 12
	s_or_b32 s55, s55, s41
	s_lshl_b32 s55, s55, 10
	v_bitop3_b32 v87, v118, s55, v119 bitop3:0xde
	global_store_dwordx4 v87, v[250:253], s[68:69]
	s_or_b32 s53, s53, 48
	s_lshr_b32 s53, s53, 3
	s_and_b32 s53, s53, 14
	s_or_b32 s53, s53, s41
	s_lshl_b32 s53, s53, 10
	v_mul_f32_e32 v224, 0xbfb8aa3b, v141
	v_mul_f32_e32 v225, v141, v141
	v_mul_f32_e32 v234, v76, v224
	v_mul_f32_e32 v235, v77, v224
	v_mul_f32_e32 v236, v78, v224
	v_mul_f32_e32 v237, v79, v224
	v_mul_f32_e32 v238, v68, v224
	v_mul_f32_e32 v239, v69, v224
	v_mul_f32_e32 v240, v70, v224
	v_mul_f32_e32 v241, v71, v224
	v_mul_f32_e32 v226, v76, v72
	v_mul_f32_e32 v227, v77, v73
	v_mul_f32_e32 v228, v78, v74
	v_mul_f32_e32 v229, v79, v75
	v_mul_f32_e32 v230, v68, v64
	v_mul_f32_e32 v231, v69, v65
	v_mul_f32_e32 v232, v70, v66
	v_mul_f32_e32 v233, v71, v67
	v_exp_f32_e32 v234, v234
	v_exp_f32_e32 v235, v235
	v_exp_f32_e32 v236, v236
	v_exp_f32_e32 v237, v237
	v_exp_f32_e32 v238, v238
	v_exp_f32_e32 v239, v239
	v_exp_f32_e32 v240, v240
	v_exp_f32_e32 v241, v241
	v_mul_f32_e32 v226, v226, v225
	v_mul_f32_e32 v227, v227, v225
	v_mul_f32_e32 v228, v228, v225
	v_mul_f32_e32 v229, v229, v225
	v_mul_f32_e32 v230, v230, v225
	v_mul_f32_e32 v231, v231, v225
	v_mul_f32_e32 v232, v232, v225
	v_mul_f32_e32 v233, v233, v225
	v_add_f32_e32 v234, 1.0, v234
	v_add_f32_e32 v235, 1.0, v235
	v_add_f32_e32 v236, 1.0, v236
	v_add_f32_e32 v237, 1.0, v237
	v_add_f32_e32 v238, 1.0, v238
	v_add_f32_e32 v239, 1.0, v239
	v_add_f32_e32 v240, 1.0, v240
	v_add_f32_e32 v241, 1.0, v241
	v_rcp_f32_e32 v234, v234
	v_rcp_f32_e32 v235, v235
	v_rcp_f32_e32 v236, v236
	v_rcp_f32_e32 v237, v237
	v_rcp_f32_e32 v238, v238
	v_rcp_f32_e32 v239, v239
	v_rcp_f32_e32 v240, v240
	v_rcp_f32_e32 v241, v241
	v_mul_f32_e32 v226, v226, v234
	v_mul_f32_e32 v227, v227, v235
	v_mul_f32_e32 v228, v228, v236
	v_mul_f32_e32 v229, v229, v237
	v_mul_f32_e32 v230, v230, v238
	v_mul_f32_e32 v231, v231, v239
	v_mul_f32_e32 v232, v232, v240
	v_mul_f32_e32 v233, v233, v241
	v_cvt_pk_bf16_f32 v242, v226, v227
	v_cvt_pk_bf16_f32 v243, v228, v229
	v_cvt_pk_bf16_f32 v244, v230, v231
	v_cvt_pk_bf16_f32 v245, v232, v233
	v_bitop3_b32 v68, v118, s53, v119 bitop3:0xde
	global_store_dwordx4 v68, v[242:245], s[68:69]
	s_andn2_b64 vcc, exec, s[4:5]
	s_mov_b64 s[4:5], -1
	v_add_u32_e32 v67, 0x80, v151
	v_ashrrev_i32_e32 v66, 7, v67
	v_mul_f32_e32 v224, 0xbfb8aa3b, v138
	v_mul_f32_e32 v225, v138, v138
	v_mul_f32_e32 v234, v60, v224
	v_mul_f32_e32 v235, v61, v224
	v_mul_f32_e32 v236, v62, v224
	v_mul_f32_e32 v237, v63, v224
	v_mul_f32_e32 v238, v52, v224
	v_mul_f32_e32 v239, v53, v224
	v_mul_f32_e32 v240, v54, v224
	v_mul_f32_e32 v241, v55, v224
	v_mul_f32_e32 v226, v60, v56
	v_mul_f32_e32 v227, v61, v57
	v_mul_f32_e32 v228, v62, v58
	v_mul_f32_e32 v229, v63, v59
	v_mul_f32_e32 v230, v52, v48
	v_mul_f32_e32 v231, v53, v49
	v_mul_f32_e32 v232, v54, v50
	v_mul_f32_e32 v233, v55, v51
	v_exp_f32_e32 v234, v234
	v_exp_f32_e32 v235, v235
	v_exp_f32_e32 v236, v236
	v_exp_f32_e32 v237, v237
	v_exp_f32_e32 v238, v238
	v_exp_f32_e32 v239, v239
	v_exp_f32_e32 v240, v240
	v_exp_f32_e32 v241, v241
	v_mul_f32_e32 v226, v226, v225
	v_mul_f32_e32 v227, v227, v225
	v_mul_f32_e32 v228, v228, v225
	v_mul_f32_e32 v229, v229, v225
	v_mul_f32_e32 v230, v230, v225
	v_mul_f32_e32 v231, v231, v225
	v_mul_f32_e32 v232, v232, v225
	v_mul_f32_e32 v233, v233, v225
	v_add_f32_e32 v234, 1.0, v234
	v_add_f32_e32 v235, 1.0, v235
	v_add_f32_e32 v236, 1.0, v236
	v_add_f32_e32 v237, 1.0, v237
	v_add_f32_e32 v238, 1.0, v238
	v_add_f32_e32 v239, 1.0, v239
	v_add_f32_e32 v240, 1.0, v240
	v_add_f32_e32 v241, 1.0, v241
	v_rcp_f32_e32 v234, v234
	v_rcp_f32_e32 v235, v235
	v_rcp_f32_e32 v236, v236
	v_rcp_f32_e32 v237, v237
	v_rcp_f32_e32 v238, v238
	v_rcp_f32_e32 v239, v239
	v_rcp_f32_e32 v240, v240
	v_rcp_f32_e32 v241, v241
	v_mul_f32_e32 v226, v226, v234
	v_mul_f32_e32 v227, v227, v235
	v_mul_f32_e32 v228, v228, v236
	v_mul_f32_e32 v229, v229, v237
	v_mul_f32_e32 v230, v230, v238
	v_mul_f32_e32 v231, v231, v239
	v_mul_f32_e32 v232, v232, v240
	v_mul_f32_e32 v233, v233, v241
	v_cvt_pk_bf16_f32 v246, v226, v227
	v_cvt_pk_bf16_f32 v247, v228, v229
	v_cvt_pk_bf16_f32 v248, v230, v231
	v_cvt_pk_bf16_f32 v249, v232, v233
	v_lshlrev_b32_e32 v55, 2, v67
	v_and_b32_e32 v55, 32, v55
	v_lshlrev_b32_e32 v54, 6, v67
	v_and_or_b32 v54, v54, s40, v143
	v_bitop3_b32 v130, v54, s42, v55 bitop3:0xde
; __host__ __device__ __forceinline__ size_t tiled_off(int row, int col, int K) { return ((size_t)(row >> 7) * (K >> 6) + (col >> 6)) * 8192 + (lds_byte(row & 127, col & 63) >> 1); }
; __device__ __forceinline__ unsigned cvt_pk_bf16(float lo, float hi) { unsigned r; asm volatile("v_cvt_pk_bf16_f32 %0, %1, %2" : "=v"(r) : "v"(lo), "v"(hi)); return r; }
; __device__ __forceinline__ float fast_sigmoid(float x) { return __builtin_amdgcn_rcpf(1.0f + __builtin_amdgcn_exp2f(x * -1.4426950408889634f)); }
;     __device__ __forceinline__ void operator()(const f32x4 (&acc)[2][2][4][2], const Unit& u, int wr, int wc, int fr, int fq, const PG8_LAS float* rtab) const {
;         const int row0 = u.pm * BM + wr * 64 + fr, lcol = u.pn * HALF + wc * 32 + 8 * fq;
;         float rs[2][4]; load_rstd(rtab, wr, fr, rs);
;         f32x4 bv[2], bg[2];
; #pragma unroll
;         for (int n = 0; n < 2; ++n) { bv[n] = (MODE == 0) ? *(const f32x4*)(b0 + lcol + 4 * n) : (f32x4){0.f, 0.f, 0.f, 0.f}; bg[n] = (MODE == 0) ? *(const f32x4*)(b1 + lcol + 4 * n) : (f32x4){0.f, 0.f, 0.f, 0.f}; }
; #pragma unroll
;         for (int ai = 0; ai < 2; ++ai)
; #pragma unroll
;             for (int m = 0; m < 4; ++m) { const float r = rs[ai][m]; float o[8];
; #pragma unroll
;                 for (int n = 0; n < 2; ++n) { const f32x4 a = acc[ai][0][m][n] * r + bv[n], g = acc[ai][1][m][n] * r + bg[n];
; #pragma unroll
;                     for (int e = 0; e < 4; ++e) o[4 * n + e] = (MODE == 0) ? a[e] * fast_sigmoid(g[e]) : a[e] * fast_sigmoid(a[e]) * g[e]; }
;                 u32x4 w; w.x = cvt_pk_bf16(o[0], o[1]); w.y = cvt_pk_bf16(o[2], o[3]); w.z = cvt_pk_bf16(o[4], o[5]); w.w = cvt_pk_bf16(o[6], o[7]);
;                 if (MODE == 1) *(u32x4*)(O + tiled_off(row0 + ai * HALF + m * 16, lcol, ldc)) = w;
	v_mul_lo_u32 v48, v66, 44
	v_ashrrev_i32_e32 v49, 31, v48
	v_lshl_add_u64 v[48:49], v[48:49], 0, s[60:61]
	v_lshlrev_b64 v[48:49], 14, v[48:49]
	v_lshl_add_u64 v[48:49], s[14:15], 0, v[48:49]
	v_lshl_add_u64 v[56:57], v[48:49], 0, v[130:131]
	global_store_dwordx4 v[56:57], v[246:249], off
	s_nop 0
	v_mul_f32_e32 v224, 0xbfb8aa3b, v139
	v_mul_f32_e32 v225, v139, v139
	v_mul_f32_e32 v234, v44, v224
	v_mul_f32_e32 v235, v45, v224
	v_mul_f32_e32 v236, v46, v224
	v_mul_f32_e32 v237, v47, v224
	v_mul_f32_e32 v238, v36, v224
	v_mul_f32_e32 v239, v37, v224
	v_mul_f32_e32 v240, v38, v224
	v_mul_f32_e32 v241, v39, v224
	v_mul_f32_e32 v226, v44, v40
	v_mul_f32_e32 v227, v45, v41
	v_mul_f32_e32 v228, v46, v42
	v_mul_f32_e32 v229, v47, v43
	v_mul_f32_e32 v230, v36, v32
	v_mul_f32_e32 v231, v37, v33
	v_mul_f32_e32 v232, v38, v34
	v_mul_f32_e32 v233, v39, v35
	v_exp_f32_e32 v234, v234
	v_exp_f32_e32 v235, v235
	v_exp_f32_e32 v236, v236
	v_exp_f32_e32 v237, v237
	v_exp_f32_e32 v238, v238
	v_exp_f32_e32 v239, v239
	v_exp_f32_e32 v240, v240
	v_exp_f32_e32 v241, v241
	v_mul_f32_e32 v226, v226, v225
	v_mul_f32_e32 v227, v227, v225
	v_mul_f32_e32 v228, v228, v225
	v_mul_f32_e32 v229, v229, v225
	v_mul_f32_e32 v230, v230, v225
	v_mul_f32_e32 v231, v231, v225
	v_mul_f32_e32 v232, v232, v225
	v_mul_f32_e32 v233, v233, v225
	v_add_f32_e32 v234, 1.0, v234
	v_add_f32_e32 v235, 1.0, v235
	v_add_f32_e32 v236, 1.0, v236
	v_add_f32_e32 v237, 1.0, v237
	v_add_f32_e32 v238, 1.0, v238
	v_add_f32_e32 v239, 1.0, v239
	v_add_f32_e32 v240, 1.0, v240
	v_add_f32_e32 v241, 1.0, v241
	v_rcp_f32_e32 v234, v234
	v_rcp_f32_e32 v235, v235
	v_rcp_f32_e32 v236, v236
	v_rcp_f32_e32 v237, v237
	v_rcp_f32_e32 v238, v238
	v_rcp_f32_e32 v239, v239
	v_rcp_f32_e32 v240, v240
	v_rcp_f32_e32 v241, v241
	v_mul_f32_e32 v226, v226, v234
	v_mul_f32_e32 v227, v227, v235
	v_mul_f32_e32 v228, v228, v236
	v_mul_f32_e32 v229, v229, v237
	v_mul_f32_e32 v230, v230, v238
	v_mul_f32_e32 v231, v231, v239
	v_mul_f32_e32 v232, v232, v240
	v_mul_f32_e32 v233, v233, v241
	v_cvt_pk_bf16_f32 v250, v226, v227
	v_cvt_pk_bf16_f32 v251, v228, v229
	v_cvt_pk_bf16_f32 v252, v230, v231
	v_cvt_pk_bf16_f32 v253, v232, v233
	v_add_u32_e32 v36, 0x90, v151
	v_lshrrev_b32_e32 v37, 3, v36
	v_and_or_b32 v37, v37, 10, s41
	v_lshlrev_b32_e32 v38, 6, v36
	v_lshlrev_b32_e32 v36, 2, v36
	v_and_or_b32 v38, v38, s40, v143
	v_lshlrev_b32_e32 v37, 10, v37
	v_and_b32_e32 v36, 32, v36
	v_bitop3_b32 v130, v38, v37, v36 bitop3:0xde
	v_mul_f32_e32 v224, 0xbfb8aa3b, v136
	v_mul_f32_e32 v225, v136, v136
	v_mul_f32_e32 v234, v28, v224
	v_mul_f32_e32 v235, v29, v224
	v_mul_f32_e32 v236, v30, v224
	v_mul_f32_e32 v237, v31, v224
	v_mul_f32_e32 v238, v20, v224
	v_mul_f32_e32 v239, v21, v224
	v_mul_f32_e32 v240, v22, v224
	v_mul_f32_e32 v241, v23, v224
	v_mul_f32_e32 v226, v28, v24
	v_mul_f32_e32 v227, v29, v25
	v_mul_f32_e32 v228, v30, v26
	v_mul_f32_e32 v229, v31, v27
	v_mul_f32_e32 v230, v20, v16
	v_mul_f32_e32 v231, v21, v17
	v_mul_f32_e32 v232, v22, v18
	v_mul_f32_e32 v233, v23, v19
	v_exp_f32_e32 v234, v234
	v_exp_f32_e32 v235, v235
	v_exp_f32_e32 v236, v236
	v_exp_f32_e32 v237, v237
	v_exp_f32_e32 v238, v238
	v_exp_f32_e32 v239, v239
	v_exp_f32_e32 v240, v240
	v_exp_f32_e32 v241, v241
	v_mul_f32_e32 v226, v226, v225
	v_mul_f32_e32 v227, v227, v225
	v_mul_f32_e32 v228, v228, v225
	v_mul_f32_e32 v229, v229, v225
	v_mul_f32_e32 v230, v230, v225
	v_mul_f32_e32 v231, v231, v225
	v_mul_f32_e32 v232, v232, v225
	v_mul_f32_e32 v233, v233, v225
	v_add_f32_e32 v234, 1.0, v234
	v_add_f32_e32 v235, 1.0, v235
	v_add_f32_e32 v236, 1.0, v236
	v_add_f32_e32 v237, 1.0, v237
	v_add_f32_e32 v238, 1.0, v238
	v_add_f32_e32 v239, 1.0, v239
	v_add_f32_e32 v240, 1.0, v240
	v_add_f32_e32 v241, 1.0, v241
	v_rcp_f32_e32 v234, v234
	v_rcp_f32_e32 v235, v235
	v_rcp_f32_e32 v236, v236
	v_rcp_f32_e32 v237, v237
	v_rcp_f32_e32 v238, v238
	v_rcp_f32_e32 v239, v239
	v_rcp_f32_e32 v240, v240
	v_rcp_f32_e32 v241, v241
	v_mul_f32_e32 v226, v226, v234
	v_mul_f32_e32 v227, v227, v235
	v_mul_f32_e32 v228, v228, v236
; __host__ __device__ __forceinline__ size_t tiled_off(int row, int col, int K) { return ((size_t)(row >> 7) * (K >> 6) + (col >> 6)) * 8192 + (lds_byte(row & 127, col & 63) >> 1); }
; __device__ __forceinline__ unsigned cvt_pk_bf16(float lo, float hi) { unsigned r; asm volatile("v_cvt_pk_bf16_f32 %0, %1, %2" : "=v"(r) : "v"(lo), "v"(hi)); return r; }
; __device__ __forceinline__ float fast_sigmoid(float x) { return __builtin_amdgcn_rcpf(1.0f + __builtin_amdgcn_exp2f(x * -1.4426950408889634f)); }
;     __device__ __forceinline__ void operator()(const f32x4 (&acc)[2][2][4][2], const Unit& u, int wr, int wc, int fr, int fq, const PG8_LAS float* rtab) const {
;         const int row0 = u.pm * BM + wr * 64 + fr, lcol = u.pn * HALF + wc * 32 + 8 * fq;
;         float rs[2][4]; load_rstd(rtab, wr, fr, rs);
;         f32x4 bv[2], bg[2];
; #pragma unroll
;         for (int n = 0; n < 2; ++n) { bv[n] = (MODE == 0) ? *(const f32x4*)(b0 + lcol + 4 * n) : (f32x4){0.f, 0.f, 0.f, 0.f}; bg[n] = (MODE == 0) ? *(const f32x4*)(b1 + lcol + 4 * n) : (f32x4){0.f, 0.f, 0.f, 0.f}; }
; #pragma unroll
;         for (int ai = 0; ai < 2; ++ai)
; #pragma unroll
;             for (int m = 0; m < 4; ++m) { const float r = rs[ai][m]; float o[8];
; #pragma unroll
;                 for (int n = 0; n < 2; ++n) { const f32x4 a = acc[ai][0][m][n] * r + bv[n], g = acc[ai][1][m][n] * r + bg[n];
; #pragma unroll
;                     for (int e = 0; e < 4; ++e) o[4 * n + e] = (MODE == 0) ? a[e] * fast_sigmoid(g[e]) : a[e] * fast_sigmoid(a[e]) * g[e]; }
;                 u32x4 w; w.x = cvt_pk_bf16(o[0], o[1]); w.y = cvt_pk_bf16(o[2], o[3]); w.z = cvt_pk_bf16(o[4], o[5]); w.w = cvt_pk_bf16(o[6], o[7]);
;                 if (MODE == 1) *(u32x4*)(O + tiled_off(row0 + ai * HALF + m * 16, lcol, ldc)) = w;
;                 else *(u32x4*)(O + (size_t)(row0 + ai * HALF + m * 16) * ldc + lcol) = w; }
	v_mul_f32_e32 v229, v229, v237
	v_mul_f32_e32 v230, v230, v238
	v_mul_f32_e32 v231, v231, v239
	v_mul_f32_e32 v232, v232, v240
	v_mul_f32_e32 v233, v233, v241
	v_cvt_pk_bf16_f32 v242, v226, v227
	v_cvt_pk_bf16_f32 v243, v228, v229
	v_cvt_pk_bf16_f32 v244, v230, v231
	v_cvt_pk_bf16_f32 v245, v232, v233
	v_lshl_add_u64 v[28:29], v[48:49], 0, v[130:131]
	global_store_dwordx4 v[28:29], v[250:253], off
	v_add_u32_e32 v20, 0xa0, v151
	v_lshrrev_b32_e32 v21, 3, v20
	v_and_or_b32 v21, v21, 12, s41
	v_lshlrev_b32_e32 v22, 6, v20
	v_lshlrev_b32_e32 v20, 2, v20
	v_and_or_b32 v22, v22, s40, v143
	v_lshlrev_b32_e32 v21, 10, v21
	v_and_b32_e32 v20, 32, v20
	v_bitop3_b32 v130, v22, v21, v20 bitop3:0xde
	v_lshl_add_u64 v[22:23], v[48:49], 0, v[130:131]
	global_store_dwordx4 v[22:23], v[242:245], off
	v_mul_f32_e32 v224, 0xbfb8aa3b, v137
	v_mul_f32_e32 v225, v137, v137
	v_mul_f32_e32 v234, v12, v224
	v_mul_f32_e32 v235, v13, v224
	v_mul_f32_e32 v236, v14, v224
	v_mul_f32_e32 v237, v15, v224
	v_mul_f32_e32 v238, v4, v224
	v_mul_f32_e32 v239, v5, v224
	v_mul_f32_e32 v240, v6, v224
	v_mul_f32_e32 v241, v7, v224
	v_mul_f32_e32 v226, v12, v8
	v_mul_f32_e32 v227, v13, v9
	v_mul_f32_e32 v228, v14, v10
	v_mul_f32_e32 v229, v15, v11
	v_mul_f32_e32 v230, v4, v0
	v_mul_f32_e32 v231, v5, v1
	v_mul_f32_e32 v232, v6, v2
	v_mul_f32_e32 v233, v7, v3
	v_exp_f32_e32 v234, v234
	v_exp_f32_e32 v235, v235
	v_exp_f32_e32 v236, v236
	v_exp_f32_e32 v237, v237
	v_exp_f32_e32 v238, v238
	v_exp_f32_e32 v239, v239
	v_exp_f32_e32 v240, v240
	v_exp_f32_e32 v241, v241
	v_mul_f32_e32 v226, v226, v225
	v_mul_f32_e32 v227, v227, v225
	v_mul_f32_e32 v228, v228, v225
	v_mul_f32_e32 v229, v229, v225
	v_mul_f32_e32 v230, v230, v225
	v_mul_f32_e32 v231, v231, v225
	v_mul_f32_e32 v232, v232, v225
	v_mul_f32_e32 v233, v233, v225
	v_add_f32_e32 v234, 1.0, v234
	v_add_f32_e32 v235, 1.0, v235
	v_add_f32_e32 v236, 1.0, v236
	v_add_f32_e32 v237, 1.0, v237
	v_add_f32_e32 v238, 1.0, v238
	v_add_f32_e32 v239, 1.0, v239
	v_add_f32_e32 v240, 1.0, v240
	v_add_f32_e32 v241, 1.0, v241
	v_rcp_f32_e32 v234, v234
	v_rcp_f32_e32 v235, v235
	v_rcp_f32_e32 v236, v236
	v_rcp_f32_e32 v237, v237
	v_rcp_f32_e32 v238, v238
	v_rcp_f32_e32 v239, v239
	v_rcp_f32_e32 v240, v240
	v_rcp_f32_e32 v241, v241
	v_mul_f32_e32 v226, v226, v234
	v_mul_f32_e32 v227, v227, v235
	v_mul_f32_e32 v228, v228, v236
	v_mul_f32_e32 v229, v229, v237
	v_mul_f32_e32 v230, v230, v238
	v_mul_f32_e32 v231, v231, v239
	v_mul_f32_e32 v232, v232, v240
	v_mul_f32_e32 v233, v233, v241
	v_cvt_pk_bf16_f32 v246, v226, v227
	v_cvt_pk_bf16_f32 v247, v228, v229
	v_cvt_pk_bf16_f32 v248, v230, v231
	v_cvt_pk_bf16_f32 v249, v232, v233
	v_add_u32_e32 v4, 0xb0, v151
	v_lshrrev_b32_e32 v5, 3, v4
	v_and_or_b32 v5, v5, 14, s41
	v_lshlrev_b32_e32 v6, 6, v4
	v_lshlrev_b32_e32 v4, 2, v4
	v_and_or_b32 v6, v6, s40, v143
	v_lshlrev_b32_e32 v5, 10, v5
	v_and_b32_e32 v4, 32, v4
	v_bitop3_b32 v130, v6, v5, v4 bitop3:0xde
	v_lshl_add_u64 v[4:5], v[48:49], 0, v[130:131]
	global_store_dwordx4 v[4:5], v[246:249], off
	s_cbranch_vccnz .LBB0_786
	s_and_saveexec_b64 s[4:5], s[2:3]
	s_cbranch_execz .LBB0_796
	v_lshl_or_b32 v0, s54, 8, v208
	v_ashrrev_i32_e32 v1, 31, v0
	v_lshlrev_b64 v[0:1], 6, v[0:1]
	v_lshl_add_u64 v[12:13], s[24:25], 0, v[0:1]
	global_load_dwordx4 v[0:3], v[12:13], off
	global_load_dwordx4 v[4:7], v[12:13], off offset:16
	global_load_dwordx4 v[8:11], v[12:13], off offset:32
	s_nop 0
	global_load_dwordx4 v[12:15], v[12:13], off offset:48
	s_lshl_b32 s53, s78, 10
	s_and_b32 s53, s53, 0x400
	s_waitcnt vmcnt(0)
	v_pk_add_f32 v[2:3], v[2:3], v[6:7]
	v_pk_add_f32 v[0:1], v[0:1], v[4:5]
	v_pk_add_f32 v[4:5], v[10:11], v[14:15]
	v_pk_add_f32 v[6:7], v[8:9], v[12:13]
	v_pk_add_f32 v[2:3], v[2:3], v[4:5]
	v_pk_add_f32 v[0:1], v[0:1], v[6:7]
	s_nop 0
	v_pk_mov_b32 v[4:5], v[0:1], v[2:3] op_sel:[1,0]
	v_mov_b32_e32 v1, v3
	v_pk_add_f32 v[0:1], v[4:5], v[0:1]
	s_nop 0
	v_add_f32_e32 v0, v0, v1
	v_fmamk_f32 v0, v0, 0x3a800000, v150
	v_rsq_f32_e32 v0, v0
	v_add_u32_e32 v1, s53, v145
	ds_write_b32 v1, v0

; __host__ __device__ __forceinline__ size_t tiled_off(int row, int col, int K) { return ((size_t)(row >> 7) * (K >> 6) + (col >> 6)) * 8192 + (lds_byte(row & 127, col & 63) >> 1); }
; __device__ __forceinline__ unsigned cvt_pk_bf16(float lo, float hi) { unsigned r; asm volatile("v_cvt_pk_bf16_f32 %0, %1, %2" : "=v"(r) : "v"(lo), "v"(hi)); return r; }
; __device__ __forceinline__ float fast_sigmoid(float x) { return __builtin_amdgcn_rcpf(1.0f + __builtin_amdgcn_exp2f(x * -1.4426950408889634f)); }
;     __device__ __forceinline__ void operator()(const f32x4 (&acc)[2][2][4][2], const Unit& u, int wr, int wc, int fr, int fq, const PG8_LAS float* rtab) const {
;         const int row0 = u.pm * BM + wr * 64 + fr, lcol = u.pn * HALF + wc * 32 + 8 * fq;
;         float rs[2][4]; load_rstd(rtab, wr, fr, rs);
;         f32x4 bv[2], bg[2];
; #pragma unroll
;         for (int n = 0; n < 2; ++n) { bv[n] = (MODE == 0) ? *(const f32x4*)(b0 + lcol + 4 * n) : (f32x4){0.f, 0.f, 0.f, 0.f}; bg[n] = (MODE == 0) ? *(const f32x4*)(b1 + lcol + 4 * n) : (f32x4){0.f, 0.f, 0.f, 0.f}; }
; #pragma unroll
;         for (int ai = 0; ai < 2; ++ai)
; #pragma unroll
;             for (int m = 0; m < 4; ++m) { const float r = rs[ai][m]; float o[8];
; #pragma unroll
;                 for (int n = 0; n < 2; ++n) { const f32x4 a = acc[ai][0][m][n] * r + bv[n], g = acc[ai][1][m][n] * r + bg[n];
; #pragma unroll
;                     for (int e = 0; e < 4; ++e) o[4 * n + e] = (MODE == 0) ? a[e] * fast_sigmoid(g[e]) : a[e] * fast_sigmoid(a[e]) * g[e]; }
;                 u32x4 w; w.x = cvt_pk_bf16(o[0], o[1]); w.y = cvt_pk_bf16(o[2], o[3]); w.z = cvt_pk_bf16(o[4], o[5]); w.w = cvt_pk_bf16(o[6], o[7]);
;                 if (MODE == 1) *(u32x4*)(O + tiled_off(row0 + ai * HALF + m * 16, lcol, ldc)) = w;
.LBB0_1628:
	s_lshl_b32 s45, s53, 10
	s_and_b32 s47, s45, 0x400
	v_add_u32_e32 v130, s47, v146
	ds_read2_b32 v[152:153], v130 offset1:16
	ds_read2_b32 v[140:141], v130 offset0:32 offset1:48
	ds_read2_b32 v[138:139], v130 offset0:128 offset1:144
	ds_read2_b32 v[136:137], v130 offset0:160 offset1:176
	s_waitcnt lgkmcnt(0)
	s_lshl_b32 s45, s52, 8
	s_add_i32 s45, s45, s62
	v_or_b32_e32 v151, s45, v142
	v_mul_f32_e32 v224, 0xbfb8aa3b, v152
	v_mul_f32_e32 v225, v152, v152
	v_mul_f32_e32 v234, v124, v224
	v_mul_f32_e32 v235, v125, v224
	v_mul_f32_e32 v236, v126, v224
	v_mul_f32_e32 v237, v127, v224
	v_mul_f32_e32 v238, v116, v224
	v_mul_f32_e32 v239, v117, v224
	v_mul_f32_e32 v240, v118, v224
	v_mul_f32_e32 v241, v119, v224
	v_mul_f32_e32 v226, v124, v120
	v_mul_f32_e32 v227, v125, v121
	v_mul_f32_e32 v228, v126, v122
	v_mul_f32_e32 v229, v127, v123
	v_mul_f32_e32 v230, v116, v112
	v_mul_f32_e32 v231, v117, v113
	v_mul_f32_e32 v232, v118, v114
	v_mul_f32_e32 v233, v119, v115
	v_exp_f32_e32 v234, v234
	v_exp_f32_e32 v235, v235
	v_exp_f32_e32 v236, v236
	v_exp_f32_e32 v237, v237
	v_exp_f32_e32 v238, v238
	v_exp_f32_e32 v239, v239
	v_exp_f32_e32 v240, v240
	v_exp_f32_e32 v241, v241
	v_mul_f32_e32 v226, v226, v225
	v_mul_f32_e32 v227, v227, v225
	v_mul_f32_e32 v228, v228, v225
	v_mul_f32_e32 v229, v229, v225
	v_mul_f32_e32 v230, v230, v225
	v_mul_f32_e32 v231, v231, v225
	v_mul_f32_e32 v232, v232, v225
	v_mul_f32_e32 v233, v233, v225
	v_add_f32_e32 v234, 1.0, v234
	v_add_f32_e32 v235, 1.0, v235
	v_add_f32_e32 v236, 1.0, v236
	v_add_f32_e32 v237, 1.0, v237
	v_add_f32_e32 v238, 1.0, v238
	v_add_f32_e32 v239, 1.0, v239
	v_add_f32_e32 v240, 1.0, v240
	v_add_f32_e32 v241, 1.0, v241
	v_rcp_f32_e32 v234, v234
	v_rcp_f32_e32 v235, v235
	v_rcp_f32_e32 v236, v236
	v_rcp_f32_e32 v237, v237
	v_rcp_f32_e32 v238, v238
	v_rcp_f32_e32 v239, v239
	v_rcp_f32_e32 v240, v240
	v_rcp_f32_e32 v241, v241
	v_mul_f32_e32 v226, v226, v234
	v_mul_f32_e32 v227, v227, v235
	v_mul_f32_e32 v228, v228, v236
	v_mul_f32_e32 v229, v229, v237
	v_mul_f32_e32 v230, v230, v238
	v_mul_f32_e32 v231, v231, v239
	v_mul_f32_e32 v232, v232, v240
	v_mul_f32_e32 v233, v233, v241
	v_cvt_pk_bf16_f32 v242, v226, v227
	v_cvt_pk_bf16_f32 v243, v228, v229
	v_cvt_pk_bf16_f32 v244, v230, v231
	v_cvt_pk_bf16_f32 v245, v232, v233
	v_lshlrev_b32_e32 v116, 6, v151
	v_and_or_b32 v118, v116, s64, v143
	v_lshlrev_b32_e32 v116, 2, v151
	v_and_b32_e32 v119, 32, v116
	s_lshl_b32 s47, s54, 7
	s_or_b32 s47, s47, s63
	s_ashr_i32 s52, s47, 6
	s_ashr_i32 s47, s45, 7
	s_mul_i32 s47, s47, 44
	s_ashr_i32 s53, s52, 31
	s_ashr_i32 s55, s47, 31
	s_add_u32 s54, s47, s52
	s_addc_u32 s55, s55, s53
	s_lshl_b64 s[54:55], s[54:55], 14
	s_add_u32 s54, s24, s54
	v_bitop3_b32 v120, v118, s66, v119 bitop3:0xde
	s_addc_u32 s55, s25, s55
	global_store_dwordx4 v120, v[242:245], s[54:55]
	s_or_b32 s47, s45, 16
	s_lshr_b32 s47, s47, 3
	s_and_b32 s47, s47, 10
	s_or_b32 s47, s47, s65
	s_lshl_b32 s47, s47, 10
	v_mul_f32_e32 v224, 0xbfb8aa3b, v140
	v_mul_f32_e32 v225, v140, v140
	v_mul_f32_e32 v234, v92, v224
	v_mul_f32_e32 v235, v93, v224
	v_mul_f32_e32 v236, v94, v224
	v_mul_f32_e32 v237, v95, v224
	v_mul_f32_e32 v238, v84, v224
	v_mul_f32_e32 v239, v85, v224
	v_mul_f32_e32 v240, v86, v224
	v_mul_f32_e32 v241, v87, v224
	v_mul_f32_e32 v226, v92, v88
	v_mul_f32_e32 v227, v93, v89
	v_mul_f32_e32 v228, v94, v90
	v_mul_f32_e32 v229, v95, v91
	v_mul_f32_e32 v230, v84, v80
	v_mul_f32_e32 v231, v85, v81
	v_mul_f32_e32 v232, v86, v82
	v_mul_f32_e32 v233, v87, v83
	v_exp_f32_e32 v234, v234
	v_exp_f32_e32 v235, v235
	v_exp_f32_e32 v236, v236
	v_exp_f32_e32 v237, v237
	v_exp_f32_e32 v238, v238
	v_exp_f32_e32 v239, v239
	v_exp_f32_e32 v240, v240
	v_exp_f32_e32 v241, v241
	v_mul_f32_e32 v226, v226, v225
	v_mul_f32_e32 v227, v227, v225
	v_mul_f32_e32 v228, v228, v225
	v_mul_f32_e32 v229, v229, v225
	v_mul_f32_e32 v230, v230, v225
	v_mul_f32_e32 v231, v231, v225
	v_mul_f32_e32 v232, v232, v225
	v_mul_f32_e32 v233, v233, v225
	v_add_f32_e32 v234, 1.0, v234
	v_add_f32_e32 v235, 1.0, v235
	v_add_f32_e32 v236, 1.0, v236
	v_add_f32_e32 v237, 1.0, v237
	v_add_f32_e32 v238, 1.0, v238
	v_add_f32_e32 v239, 1.0, v239
	v_add_f32_e32 v240, 1.0, v240
	v_add_f32_e32 v241, 1.0, v241
	v_rcp_f32_e32 v234, v234
	v_rcp_f32_e32 v235, v235
	v_rcp_f32_e32 v236, v236
	v_rcp_f32_e32 v237, v237
	v_rcp_f32_e32 v238, v238
	v_rcp_f32_e32 v239, v239
	v_rcp_f32_e32 v240, v240
	v_rcp_f32_e32 v241, v241
	v_mul_f32_e32 v226, v226, v234
	v_mul_f32_e32 v227, v227, v235
	v_mul_f32_e32 v228, v228, v236
	v_mul_f32_e32 v229, v229, v237
	v_mul_f32_e32 v230, v230, v238
	v_mul_f32_e32 v231, v231, v239
	v_mul_f32_e32 v232, v232, v240
	v_mul_f32_e32 v233, v233, v241
	v_cvt_pk_bf16_f32 v250, v226, v227
	v_cvt_pk_bf16_f32 v251, v228, v229
	v_cvt_pk_bf16_f32 v252, v230, v231
	v_cvt_pk_bf16_f32 v253, v232, v233
	v_bitop3_b32 v93, v118, s47, v119 bitop3:0xde
	v_mul_f32_e32 v224, 0xbfb8aa3b, v153
	v_mul_f32_e32 v225, v153, v153
	v_mul_f32_e32 v234, v108, v224
	v_mul_f32_e32 v235, v109, v224
	v_mul_f32_e32 v236, v110, v224
	v_mul_f32_e32 v237, v111, v224
	v_mul_f32_e32 v238, v100, v224
	v_mul_f32_e32 v239, v101, v224
	v_mul_f32_e32 v240, v102, v224
	v_mul_f32_e32 v241, v103, v224
	v_mul_f32_e32 v226, v108, v104
	v_mul_f32_e32 v227, v109, v105
	v_mul_f32_e32 v228, v110, v106
	v_mul_f32_e32 v229, v111, v107
	v_mul_f32_e32 v230, v100, v96
	v_mul_f32_e32 v231, v101, v97
	v_mul_f32_e32 v232, v102, v98
	v_mul_f32_e32 v233, v103, v99
	v_exp_f32_e32 v234, v234
	v_exp_f32_e32 v235, v235
	v_exp_f32_e32 v236, v236
	v_exp_f32_e32 v237, v237
	v_exp_f32_e32 v238, v238
	v_exp_f32_e32 v239, v239
	v_exp_f32_e32 v240, v240
; __host__ __device__ __forceinline__ size_t tiled_off(int row, int col, int K) { return ((size_t)(row >> 7) * (K >> 6) + (col >> 6)) * 8192 + (lds_byte(row & 127, col & 63) >> 1); }
; __device__ __forceinline__ unsigned cvt_pk_bf16(float lo, float hi) { unsigned r; asm volatile("v_cvt_pk_bf16_f32 %0, %1, %2" : "=v"(r) : "v"(lo), "v"(hi)); return r; }
; __device__ __forceinline__ float fast_sigmoid(float x) { return __builtin_amdgcn_rcpf(1.0f + __builtin_amdgcn_exp2f(x * -1.4426950408889634f)); }
;     __device__ __forceinline__ void operator()(const f32x4 (&acc)[2][2][4][2], const Unit& u, int wr, int wc, int fr, int fq, const PG8_LAS float* rtab) const {
;         const int row0 = u.pm * BM + wr * 64 + fr, lcol = u.pn * HALF + wc * 32 + 8 * fq;
;         float rs[2][4]; load_rstd(rtab, wr, fr, rs);
;         f32x4 bv[2], bg[2];
; #pragma unroll
;         for (int n = 0; n < 2; ++n) { bv[n] = (MODE == 0) ? *(const f32x4*)(b0 + lcol + 4 * n) : (f32x4){0.f, 0.f, 0.f, 0.f}; bg[n] = (MODE == 0) ? *(const f32x4*)(b1 + lcol + 4 * n) : (f32x4){0.f, 0.f, 0.f, 0.f}; }
; #pragma unroll
;         for (int ai = 0; ai < 2; ++ai)
; #pragma unroll
;             for (int m = 0; m < 4; ++m) { const float r = rs[ai][m]; float o[8];
; #pragma unroll
;                 for (int n = 0; n < 2; ++n) { const f32x4 a = acc[ai][0][m][n] * r + bv[n], g = acc[ai][1][m][n] * r + bg[n];
; #pragma unroll
;                     for (int e = 0; e < 4; ++e) o[4 * n + e] = (MODE == 0) ? a[e] * fast_sigmoid(g[e]) : a[e] * fast_sigmoid(a[e]) * g[e]; }
;                 u32x4 w; w.x = cvt_pk_bf16(o[0], o[1]); w.y = cvt_pk_bf16(o[2], o[3]); w.z = cvt_pk_bf16(o[4], o[5]); w.w = cvt_pk_bf16(o[6], o[7]);
;                 if (MODE == 1) *(u32x4*)(O + tiled_off(row0 + ai * HALF + m * 16, lcol, ldc)) = w;
	v_exp_f32_e32 v241, v241
	v_mul_f32_e32 v226, v226, v225
	v_mul_f32_e32 v227, v227, v225
	v_mul_f32_e32 v228, v228, v225
	v_mul_f32_e32 v229, v229, v225
	v_mul_f32_e32 v230, v230, v225
	v_mul_f32_e32 v231, v231, v225
	v_mul_f32_e32 v232, v232, v225
	v_mul_f32_e32 v233, v233, v225
	v_add_f32_e32 v234, 1.0, v234
	v_add_f32_e32 v235, 1.0, v235
	v_add_f32_e32 v236, 1.0, v236
	v_add_f32_e32 v237, 1.0, v237
	v_add_f32_e32 v238, 1.0, v238
	v_add_f32_e32 v239, 1.0, v239
	v_add_f32_e32 v240, 1.0, v240
	v_add_f32_e32 v241, 1.0, v241
	v_rcp_f32_e32 v234, v234
	v_rcp_f32_e32 v235, v235
	v_rcp_f32_e32 v236, v236
	v_rcp_f32_e32 v237, v237
	v_rcp_f32_e32 v238, v238
	v_rcp_f32_e32 v239, v239
	v_rcp_f32_e32 v240, v240
	v_rcp_f32_e32 v241, v241
	v_mul_f32_e32 v226, v226, v234
	v_mul_f32_e32 v227, v227, v235
	v_mul_f32_e32 v228, v228, v236
	v_mul_f32_e32 v229, v229, v237
	v_mul_f32_e32 v230, v230, v238
	v_mul_f32_e32 v231, v231, v239
	v_mul_f32_e32 v232, v232, v240
	v_mul_f32_e32 v233, v233, v241
	v_cvt_pk_bf16_f32 v246, v226, v227
	v_cvt_pk_bf16_f32 v247, v228, v229
	v_cvt_pk_bf16_f32 v248, v230, v231
	v_cvt_pk_bf16_f32 v249, v232, v233
	global_store_dwordx4 v93, v[246:249], s[54:55]
	s_or_b32 s47, s45, 32
	s_lshr_b32 s47, s47, 3
	s_and_b32 s47, s47, 12
	s_or_b32 s47, s47, s65
	s_lshl_b32 s47, s47, 10
	v_bitop3_b32 v87, v118, s47, v119 bitop3:0xde
	global_store_dwordx4 v87, v[250:253], s[54:55]
	s_or_b32 s45, s45, 48
	s_lshr_b32 s45, s45, 3
	s_and_b32 s45, s45, 14
	s_or_b32 s45, s45, s65
	s_lshl_b32 s45, s45, 10
	v_mul_f32_e32 v224, 0xbfb8aa3b, v141
	v_mul_f32_e32 v225, v141, v141
	v_mul_f32_e32 v234, v76, v224
	v_mul_f32_e32 v235, v77, v224
	v_mul_f32_e32 v236, v78, v224
	v_mul_f32_e32 v237, v79, v224
	v_mul_f32_e32 v238, v68, v224
	v_mul_f32_e32 v239, v69, v224
	v_mul_f32_e32 v240, v70, v224
	v_mul_f32_e32 v241, v71, v224
	v_mul_f32_e32 v226, v76, v72
	v_mul_f32_e32 v227, v77, v73
	v_mul_f32_e32 v228, v78, v74
	v_mul_f32_e32 v229, v79, v75
	v_mul_f32_e32 v230, v68, v64
	v_mul_f32_e32 v231, v69, v65
	v_mul_f32_e32 v232, v70, v66
	v_mul_f32_e32 v233, v71, v67
	v_exp_f32_e32 v234, v234
	v_exp_f32_e32 v235, v235
	v_exp_f32_e32 v236, v236
	v_exp_f32_e32 v237, v237
	v_exp_f32_e32 v238, v238
	v_exp_f32_e32 v239, v239
	v_exp_f32_e32 v240, v240
	v_exp_f32_e32 v241, v241
	v_mul_f32_e32 v226, v226, v225
	v_mul_f32_e32 v227, v227, v225
	v_mul_f32_e32 v228, v228, v225
	v_mul_f32_e32 v229, v229, v225
	v_mul_f32_e32 v230, v230, v225
	v_mul_f32_e32 v231, v231, v225
	v_mul_f32_e32 v232, v232, v225
	v_mul_f32_e32 v233, v233, v225
	v_add_f32_e32 v234, 1.0, v234
	v_add_f32_e32 v235, 1.0, v235
	v_add_f32_e32 v236, 1.0, v236
	v_add_f32_e32 v237, 1.0, v237
	v_add_f32_e32 v238, 1.0, v238
	v_add_f32_e32 v239, 1.0, v239
	v_add_f32_e32 v240, 1.0, v240
	v_add_f32_e32 v241, 1.0, v241
	v_rcp_f32_e32 v234, v234
	v_rcp_f32_e32 v235, v235
	v_rcp_f32_e32 v236, v236
	v_rcp_f32_e32 v237, v237
	v_rcp_f32_e32 v238, v238
	v_rcp_f32_e32 v239, v239
	v_rcp_f32_e32 v240, v240
	v_rcp_f32_e32 v241, v241
	v_mul_f32_e32 v226, v226, v234
	v_mul_f32_e32 v227, v227, v235
	v_mul_f32_e32 v228, v228, v236
	v_mul_f32_e32 v229, v229, v237
	v_mul_f32_e32 v230, v230, v238
	v_mul_f32_e32 v231, v231, v239
	v_mul_f32_e32 v232, v232, v240
	v_mul_f32_e32 v233, v233, v241
	v_cvt_pk_bf16_f32 v242, v226, v227
	v_cvt_pk_bf16_f32 v243, v228, v229
	v_cvt_pk_bf16_f32 v244, v230, v231
	v_cvt_pk_bf16_f32 v245, v232, v233
	v_bitop3_b32 v68, v118, s45, v119 bitop3:0xde
	global_store_dwordx4 v68, v[242:245], s[54:55]
	s_andn2_b64 vcc, exec, s[4:5]
	s_mov_b64 s[4:5], -1
	v_add_u32_e32 v67, 0x80, v151
	v_ashrrev_i32_e32 v66, 7, v67
	v_mul_f32_e32 v224, 0xbfb8aa3b, v138
	v_mul_f32_e32 v225, v138, v138
	v_mul_f32_e32 v234, v60, v224
	v_mul_f32_e32 v235, v61, v224
	v_mul_f32_e32 v236, v62, v224
	v_mul_f32_e32 v237, v63, v224
	v_mul_f32_e32 v238, v52, v224
	v_mul_f32_e32 v239, v53, v224
	v_mul_f32_e32 v240, v54, v224
	v_mul_f32_e32 v241, v55, v224
	v_mul_f32_e32 v226, v60, v56
	v_mul_f32_e32 v227, v61, v57
	v_mul_f32_e32 v228, v62, v58
	v_mul_f32_e32 v229, v63, v59
	v_mul_f32_e32 v230, v52, v48
	v_mul_f32_e32 v231, v53, v49
	v_mul_f32_e32 v232, v54, v50
	v_mul_f32_e32 v233, v55, v51
	v_exp_f32_e32 v234, v234
	v_exp_f32_e32 v235, v235
	v_exp_f32_e32 v236, v236
	v_exp_f32_e32 v237, v237
	v_exp_f32_e32 v238, v238
	v_exp_f32_e32 v239, v239
	v_exp_f32_e32 v240, v240
	v_exp_f32_e32 v241, v241
	v_mul_f32_e32 v226, v226, v225
	v_mul_f32_e32 v227, v227, v225
	v_mul_f32_e32 v228, v228, v225
	v_mul_f32_e32 v229, v229, v225
	v_mul_f32_e32 v230, v230, v225
	v_mul_f32_e32 v231, v231, v225
	v_mul_f32_e32 v232, v232, v225
	v_mul_f32_e32 v233, v233, v225
	v_add_f32_e32 v234, 1.0, v234
	v_add_f32_e32 v235, 1.0, v235
	v_add_f32_e32 v236, 1.0, v236
	v_add_f32_e32 v237, 1.0, v237
	v_add_f32_e32 v238, 1.0, v238
	v_add_f32_e32 v239, 1.0, v239
	v_add_f32_e32 v240, 1.0, v240
	v_add_f32_e32 v241, 1.0, v241
	v_rcp_f32_e32 v234, v234
	v_rcp_f32_e32 v235, v235
	v_rcp_f32_e32 v236, v236
	v_rcp_f32_e32 v237, v237
	v_rcp_f32_e32 v238, v238
	v_rcp_f32_e32 v239, v239
	v_rcp_f32_e32 v240, v240
	v_rcp_f32_e32 v241, v241
	v_mul_f32_e32 v226, v226, v234
	v_mul_f32_e32 v227, v227, v235
	v_mul_f32_e32 v228, v228, v236
	v_mul_f32_e32 v229, v229, v237
	v_mul_f32_e32 v230, v230, v238
	v_mul_f32_e32 v231, v231, v239
	v_mul_f32_e32 v232, v232, v240
	v_mul_f32_e32 v233, v233, v241
	v_cvt_pk_bf16_f32 v246, v226, v227
	v_cvt_pk_bf16_f32 v247, v228, v229
	v_cvt_pk_bf16_f32 v248, v230, v231
	v_cvt_pk_bf16_f32 v249, v232, v233
	v_lshlrev_b32_e32 v55, 2, v67
	v_and_b32_e32 v55, 32, v55
	v_lshlrev_b32_e32 v54, 6, v67
	v_and_or_b32 v54, v54, s64, v143
	v_bitop3_b32 v130, v54, s66, v55 bitop3:0xde
; __host__ __device__ __forceinline__ size_t tiled_off(int row, int col, int K) { return ((size_t)(row >> 7) * (K >> 6) + (col >> 6)) * 8192 + (lds_byte(row & 127, col & 63) >> 1); }
; __device__ __forceinline__ unsigned cvt_pk_bf16(float lo, float hi) { unsigned r; asm volatile("v_cvt_pk_bf16_f32 %0, %1, %2" : "=v"(r) : "v"(lo), "v"(hi)); return r; }
; __device__ __forceinline__ float fast_sigmoid(float x) { return __builtin_amdgcn_rcpf(1.0f + __builtin_amdgcn_exp2f(x * -1.4426950408889634f)); }
;     __device__ __forceinline__ void operator()(const f32x4 (&acc)[2][2][4][2], const Unit& u, int wr, int wc, int fr, int fq, const PG8_LAS float* rtab) const {
;         const int row0 = u.pm * BM + wr * 64 + fr, lcol = u.pn * HALF + wc * 32 + 8 * fq;
;         float rs[2][4]; load_rstd(rtab, wr, fr, rs);
;         f32x4 bv[2], bg[2];
; #pragma unroll
;         for (int n = 0; n < 2; ++n) { bv[n] = (MODE == 0) ? *(const f32x4*)(b0 + lcol + 4 * n) : (f32x4){0.f, 0.f, 0.f, 0.f}; bg[n] = (MODE == 0) ? *(const f32x4*)(b1 + lcol + 4 * n) : (f32x4){0.f, 0.f, 0.f, 0.f}; }
; #pragma unroll
;         for (int ai = 0; ai < 2; ++ai)
; #pragma unroll
;             for (int m = 0; m < 4; ++m) { const float r = rs[ai][m]; float o[8];
; #pragma unroll
;                 for (int n = 0; n < 2; ++n) { const f32x4 a = acc[ai][0][m][n] * r + bv[n], g = acc[ai][1][m][n] * r + bg[n];
; #pragma unroll
;                     for (int e = 0; e < 4; ++e) o[4 * n + e] = (MODE == 0) ? a[e] * fast_sigmoid(g[e]) : a[e] * fast_sigmoid(a[e]) * g[e]; }
;                 u32x4 w; w.x = cvt_pk_bf16(o[0], o[1]); w.y = cvt_pk_bf16(o[2], o[3]); w.z = cvt_pk_bf16(o[4], o[5]); w.w = cvt_pk_bf16(o[6], o[7]);
;                 if (MODE == 1) *(u32x4*)(O + tiled_off(row0 + ai * HALF + m * 16, lcol, ldc)) = w;
	v_mul_lo_u32 v48, v66, 44
	v_ashrrev_i32_e32 v49, 31, v48
	v_lshl_add_u64 v[48:49], v[48:49], 0, s[52:53]
	v_lshlrev_b64 v[48:49], 14, v[48:49]
	v_lshl_add_u64 v[48:49], s[24:25], 0, v[48:49]
	v_lshl_add_u64 v[56:57], v[48:49], 0, v[130:131]
	global_store_dwordx4 v[56:57], v[246:249], off
	s_nop 0
	v_mul_f32_e32 v224, 0xbfb8aa3b, v139
	v_mul_f32_e32 v225, v139, v139
	v_mul_f32_e32 v234, v44, v224
	v_mul_f32_e32 v235, v45, v224
	v_mul_f32_e32 v236, v46, v224
	v_mul_f32_e32 v237, v47, v224
	v_mul_f32_e32 v238, v36, v224
	v_mul_f32_e32 v239, v37, v224
	v_mul_f32_e32 v240, v38, v224
	v_mul_f32_e32 v241, v39, v224
	v_mul_f32_e32 v226, v44, v40
	v_mul_f32_e32 v227, v45, v41
	v_mul_f32_e32 v228, v46, v42
	v_mul_f32_e32 v229, v47, v43
	v_mul_f32_e32 v230, v36, v32
	v_mul_f32_e32 v231, v37, v33
	v_mul_f32_e32 v232, v38, v34
	v_mul_f32_e32 v233, v39, v35
	v_exp_f32_e32 v234, v234
	v_exp_f32_e32 v235, v235
	v_exp_f32_e32 v236, v236
	v_exp_f32_e32 v237, v237
	v_exp_f32_e32 v238, v238
	v_exp_f32_e32 v239, v239
	v_exp_f32_e32 v240, v240
	v_exp_f32_e32 v241, v241
	v_mul_f32_e32 v226, v226, v225
	v_mul_f32_e32 v227, v227, v225
	v_mul_f32_e32 v228, v228, v225
	v_mul_f32_e32 v229, v229, v225
	v_mul_f32_e32 v230, v230, v225
	v_mul_f32_e32 v231, v231, v225
	v_mul_f32_e32 v232, v232, v225
	v_mul_f32_e32 v233, v233, v225
	v_add_f32_e32 v234, 1.0, v234
	v_add_f32_e32 v235, 1.0, v235
	v_add_f32_e32 v236, 1.0, v236
	v_add_f32_e32 v237, 1.0, v237
	v_add_f32_e32 v238, 1.0, v238
	v_add_f32_e32 v239, 1.0, v239
	v_add_f32_e32 v240, 1.0, v240
	v_add_f32_e32 v241, 1.0, v241
	v_rcp_f32_e32 v234, v234
	v_rcp_f32_e32 v235, v235
	v_rcp_f32_e32 v236, v236
	v_rcp_f32_e32 v237, v237
	v_rcp_f32_e32 v238, v238
	v_rcp_f32_e32 v239, v239
	v_rcp_f32_e32 v240, v240
	v_rcp_f32_e32 v241, v241
	v_mul_f32_e32 v226, v226, v234
	v_mul_f32_e32 v227, v227, v235
	v_mul_f32_e32 v228, v228, v236
	v_mul_f32_e32 v229, v229, v237
	v_mul_f32_e32 v230, v230, v238
	v_mul_f32_e32 v231, v231, v239
	v_mul_f32_e32 v232, v232, v240
	v_mul_f32_e32 v233, v233, v241
	v_cvt_pk_bf16_f32 v250, v226, v227
	v_cvt_pk_bf16_f32 v251, v228, v229
	v_cvt_pk_bf16_f32 v252, v230, v231
	v_cvt_pk_bf16_f32 v253, v232, v233
	v_add_u32_e32 v36, 0x90, v151
	v_lshrrev_b32_e32 v37, 3, v36
	v_and_or_b32 v37, v37, 10, s65
	v_lshlrev_b32_e32 v38, 6, v36
	v_lshlrev_b32_e32 v36, 2, v36
	v_and_or_b32 v38, v38, s64, v143
	v_lshlrev_b32_e32 v37, 10, v37
	v_and_b32_e32 v36, 32, v36
	v_bitop3_b32 v130, v38, v37, v36 bitop3:0xde
	v_mul_f32_e32 v224, 0xbfb8aa3b, v136
	v_mul_f32_e32 v225, v136, v136
	v_mul_f32_e32 v234, v28, v224
	v_mul_f32_e32 v235, v29, v224
	v_mul_f32_e32 v236, v30, v224
	v_mul_f32_e32 v237, v31, v224
	v_mul_f32_e32 v238, v20, v224
	v_mul_f32_e32 v239, v21, v224
	v_mul_f32_e32 v240, v22, v224
	v_mul_f32_e32 v241, v23, v224
	v_mul_f32_e32 v226, v28, v24
	v_mul_f32_e32 v227, v29, v25
	v_mul_f32_e32 v228, v30, v26
	v_mul_f32_e32 v229, v31, v27
	v_mul_f32_e32 v230, v20, v16
	v_mul_f32_e32 v231, v21, v17
	v_mul_f32_e32 v232, v22, v18
	v_mul_f32_e32 v233, v23, v19
	v_exp_f32_e32 v234, v234
	v_exp_f32_e32 v235, v235
	v_exp_f32_e32 v236, v236
	v_exp_f32_e32 v237, v237
	v_exp_f32_e32 v238, v238
	v_exp_f32_e32 v239, v239
	v_exp_f32_e32 v240, v240
	v_exp_f32_e32 v241, v241
	v_mul_f32_e32 v226, v226, v225
	v_mul_f32_e32 v227, v227, v225
	v_mul_f32_e32 v228, v228, v225
	v_mul_f32_e32 v229, v229, v225
	v_mul_f32_e32 v230, v230, v225
	v_mul_f32_e32 v231, v231, v225
	v_mul_f32_e32 v232, v232, v225
	v_mul_f32_e32 v233, v233, v225
	v_add_f32_e32 v234, 1.0, v234
	v_add_f32_e32 v235, 1.0, v235
	v_add_f32_e32 v236, 1.0, v236
	v_add_f32_e32 v237, 1.0, v237
	v_add_f32_e32 v238, 1.0, v238
	v_add_f32_e32 v239, 1.0, v239
	v_add_f32_e32 v240, 1.0, v240
	v_add_f32_e32 v241, 1.0, v241
	v_rcp_f32_e32 v234, v234
	v_rcp_f32_e32 v235, v235
	v_rcp_f32_e32 v236, v236
	v_rcp_f32_e32 v237, v237
	v_rcp_f32_e32 v238, v238
	v_rcp_f32_e32 v239, v239
	v_rcp_f32_e32 v240, v240
	v_rcp_f32_e32 v241, v241
	v_mul_f32_e32 v226, v226, v234
	v_mul_f32_e32 v227, v227, v235
	v_mul_f32_e32 v228, v228, v236
; __host__ __device__ __forceinline__ size_t tiled_off(int row, int col, int K) { return ((size_t)(row >> 7) * (K >> 6) + (col >> 6)) * 8192 + (lds_byte(row & 127, col & 63) >> 1); }
; __device__ __forceinline__ unsigned cvt_pk_bf16(float lo, float hi) { unsigned r; asm volatile("v_cvt_pk_bf16_f32 %0, %1, %2" : "=v"(r) : "v"(lo), "v"(hi)); return r; }
; __device__ __forceinline__ float fast_sigmoid(float x) { return __builtin_amdgcn_rcpf(1.0f + __builtin_amdgcn_exp2f(x * -1.4426950408889634f)); }
;     __device__ __forceinline__ void operator()(const f32x4 (&acc)[2][2][4][2], const Unit& u, int wr, int wc, int fr, int fq, const PG8_LAS float* rtab) const {
;         const int row0 = u.pm * BM + wr * 64 + fr, lcol = u.pn * HALF + wc * 32 + 8 * fq;
;         float rs[2][4]; load_rstd(rtab, wr, fr, rs);
;         f32x4 bv[2], bg[2];
; #pragma unroll
;         for (int n = 0; n < 2; ++n) { bv[n] = (MODE == 0) ? *(const f32x4*)(b0 + lcol + 4 * n) : (f32x4){0.f, 0.f, 0.f, 0.f}; bg[n] = (MODE == 0) ? *(const f32x4*)(b1 + lcol + 4 * n) : (f32x4){0.f, 0.f, 0.f, 0.f}; }
; #pragma unroll
;         for (int ai = 0; ai < 2; ++ai)
; #pragma unroll
;             for (int m = 0; m < 4; ++m) { const float r = rs[ai][m]; float o[8];
; #pragma unroll
;                 for (int n = 0; n < 2; ++n) { const f32x4 a = acc[ai][0][m][n] * r + bv[n], g = acc[ai][1][m][n] * r + bg[n];
; #pragma unroll
;                     for (int e = 0; e < 4; ++e) o[4 * n + e] = (MODE == 0) ? a[e] * fast_sigmoid(g[e]) : a[e] * fast_sigmoid(a[e]) * g[e]; }
;                 u32x4 w; w.x = cvt_pk_bf16(o[0], o[1]); w.y = cvt_pk_bf16(o[2], o[3]); w.z = cvt_pk_bf16(o[4], o[5]); w.w = cvt_pk_bf16(o[6], o[7]);
;                 if (MODE == 1) *(u32x4*)(O + tiled_off(row0 + ai * HALF + m * 16, lcol, ldc)) = w;
;                 else *(u32x4*)(O + (size_t)(row0 + ai * HALF + m * 16) * ldc + lcol) = w; }
	v_mul_f32_e32 v229, v229, v237
	v_mul_f32_e32 v230, v230, v238
	v_mul_f32_e32 v231, v231, v239
	v_mul_f32_e32 v232, v232, v240
	v_mul_f32_e32 v233, v233, v241
	v_cvt_pk_bf16_f32 v242, v226, v227
	v_cvt_pk_bf16_f32 v243, v228, v229
	v_cvt_pk_bf16_f32 v244, v230, v231
	v_cvt_pk_bf16_f32 v245, v232, v233
	v_lshl_add_u64 v[28:29], v[48:49], 0, v[130:131]
	global_store_dwordx4 v[28:29], v[250:253], off
	v_add_u32_e32 v20, 0xa0, v151
	v_lshrrev_b32_e32 v21, 3, v20
	v_and_or_b32 v21, v21, 12, s65
	v_lshlrev_b32_e32 v22, 6, v20
	v_lshlrev_b32_e32 v20, 2, v20
	v_and_or_b32 v22, v22, s64, v143
	v_lshlrev_b32_e32 v21, 10, v21
	v_and_b32_e32 v20, 32, v20
	v_bitop3_b32 v130, v22, v21, v20 bitop3:0xde
	v_lshl_add_u64 v[22:23], v[48:49], 0, v[130:131]
	global_store_dwordx4 v[22:23], v[242:245], off
	v_mul_f32_e32 v224, 0xbfb8aa3b, v137
	v_mul_f32_e32 v225, v137, v137
	v_mul_f32_e32 v234, v12, v224
	v_mul_f32_e32 v235, v13, v224
	v_mul_f32_e32 v236, v14, v224
	v_mul_f32_e32 v237, v15, v224
	v_mul_f32_e32 v238, v4, v224
	v_mul_f32_e32 v239, v5, v224
	v_mul_f32_e32 v240, v6, v224
	v_mul_f32_e32 v241, v7, v224
	v_mul_f32_e32 v226, v12, v8
	v_mul_f32_e32 v227, v13, v9
	v_mul_f32_e32 v228, v14, v10
	v_mul_f32_e32 v229, v15, v11
	v_mul_f32_e32 v230, v4, v0
	v_mul_f32_e32 v231, v5, v1
	v_mul_f32_e32 v232, v6, v2
	v_mul_f32_e32 v233, v7, v3
	v_exp_f32_e32 v234, v234
	v_exp_f32_e32 v235, v235
	v_exp_f32_e32 v236, v236
	v_exp_f32_e32 v237, v237
	v_exp_f32_e32 v238, v238
	v_exp_f32_e32 v239, v239
	v_exp_f32_e32 v240, v240
	v_exp_f32_e32 v241, v241
	v_mul_f32_e32 v226, v226, v225
	v_mul_f32_e32 v227, v227, v225
	v_mul_f32_e32 v228, v228, v225
	v_mul_f32_e32 v229, v229, v225
	v_mul_f32_e32 v230, v230, v225
	v_mul_f32_e32 v231, v231, v225
	v_mul_f32_e32 v232, v232, v225
	v_mul_f32_e32 v233, v233, v225
	v_add_f32_e32 v234, 1.0, v234
	v_add_f32_e32 v235, 1.0, v235
	v_add_f32_e32 v236, 1.0, v236
	v_add_f32_e32 v237, 1.0, v237
	v_add_f32_e32 v238, 1.0, v238
	v_add_f32_e32 v239, 1.0, v239
	v_add_f32_e32 v240, 1.0, v240
	v_add_f32_e32 v241, 1.0, v241
	v_rcp_f32_e32 v234, v234
	v_rcp_f32_e32 v235, v235
	v_rcp_f32_e32 v236, v236
	v_rcp_f32_e32 v237, v237
	v_rcp_f32_e32 v238, v238
	v_rcp_f32_e32 v239, v239
	v_rcp_f32_e32 v240, v240
	v_rcp_f32_e32 v241, v241
	v_mul_f32_e32 v226, v226, v234
	v_mul_f32_e32 v227, v227, v235
	v_mul_f32_e32 v228, v228, v236
	v_mul_f32_e32 v229, v229, v237
	v_mul_f32_e32 v230, v230, v238
	v_mul_f32_e32 v231, v231, v239
	v_mul_f32_e32 v232, v232, v240
	v_mul_f32_e32 v233, v233, v241
	v_cvt_pk_bf16_f32 v246, v226, v227
	v_cvt_pk_bf16_f32 v247, v228, v229
	v_cvt_pk_bf16_f32 v248, v230, v231
	v_cvt_pk_bf16_f32 v249, v232, v233
	v_add_u32_e32 v4, 0xb0, v151
	v_lshrrev_b32_e32 v5, 3, v4
	v_and_or_b32 v5, v5, 14, s65
	v_lshlrev_b32_e32 v6, 6, v4
	v_lshlrev_b32_e32 v4, 2, v4
	v_and_or_b32 v6, v6, s64, v143
	v_lshlrev_b32_e32 v5, 10, v5
	v_and_b32_e32 v4, 32, v4
	v_bitop3_b32 v130, v6, v5, v4 bitop3:0xde
	v_lshl_add_u64 v[4:5], v[48:49], 0, v[130:131]
	global_store_dwordx4 v[4:5], v[246:249], off
	s_cbranch_vccnz .LBB0_1621
	s_and_saveexec_b64 s[4:5], s[2:3]
	s_cbranch_execz .LBB0_1631
	v_lshl_or_b32 v0, s46, 8, v208
	v_ashrrev_i32_e32 v1, 31, v0
	v_lshlrev_b64 v[0:1], 6, v[0:1]
	v_lshl_add_u64 v[12:13], s[10:11], 0, v[0:1]
	global_load_dwordx4 v[0:3], v[12:13], off
	global_load_dwordx4 v[4:7], v[12:13], off offset:16
	global_load_dwordx4 v[8:11], v[12:13], off offset:32
	s_nop 0
	global_load_dwordx4 v[12:15], v[12:13], off offset:48
	s_lshl_b32 s45, s72, 10
	s_and_b32 s45, s45, 0x400
	s_waitcnt vmcnt(0)
	v_pk_add_f32 v[2:3], v[2:3], v[6:7]
	v_pk_add_f32 v[0:1], v[0:1], v[4:5]
	v_pk_add_f32 v[4:5], v[10:11], v[14:15]
	v_pk_add_f32 v[6:7], v[8:9], v[12:13]
	v_pk_add_f32 v[2:3], v[2:3], v[4:5]
	v_pk_add_f32 v[0:1], v[0:1], v[6:7]
	s_nop 0
	v_pk_mov_b32 v[4:5], v[0:1], v[2:3] op_sel:[1,0]
	v_mov_b32_e32 v1, v3
	v_pk_add_f32 v[0:1], v[4:5], v[0:1]
	s_nop 0
	v_add_f32_e32 v0, v0, v1
	v_fmamk_f32 v0, v0, 0x3a800000, v150
	v_rsq_f32_e32 v0, v0
	v_add_u32_e32 v1, s45, v145
	ds_write_b32 v1, v0
